# zero-fill of padded compressed row uses its own gtid compare again (was tied to the rebalanced thread id)
# baseline (speedup 1.0000x reference)
.LBB0_201:
	s_or_b64 exec, exec, s[12:13]
	s_movk_i32 s0, 0x200
	v_cmp_gt_i32_e32 vcc, s0, v43
	s_and_saveexec_b64 s[0:1], vcc
	s_cbranch_execz .LBB0_204
	s_add_u32 s8, s2, 0xd1d0000
	s_addc_u32 s9, s3, 0
	v_readlane_b32 s12, v252, 2
	s_add_u32 s10, s2, 0xd1f0000
	v_mov_b32_e32 v0, 0x1fc0
	v_lshlrev_b32_e32 v1, 7, v42
	v_readlane_b32 s13, v252, 3
	v_readlane_b32 s14, v252, 4
	v_readlane_b32 s15, v252, 5
	v_readlane_b32 s18, v252, 8
	s_addc_u32 s11, s3, 0
	v_and_or_b32 v0, v42, 63, v0
	v_lshl_add_u32 v1, s64, 15, v1
	s_lshl_b32 s14, s18, 15
	s_mov_b64 s[12:13], 0
	v_mov_b32_e32 v2, 0
	s_movk_i32 s15, 0x1ff
	v_readlane_b32 s16, v252, 6
	v_readlane_b32 s17, v252, 7
	v_readlane_b32 s19, v252, 9
